# row-statistics exchange polls (P4 x2, P6) also keep one extra poll in flight
# baseline (speedup 1.0000x reference)
.LBB0_595:
	s_or_b64 exec, exec, s[18:19]
	s_cmp_lt_u32 s47, 64
	s_cselect_b64 s[20:21], -1, 0
	s_cmp_gt_u32 s47, 63
	s_cbranch_scc1 .LBB0_611
	s_memrealtime s[18:19]
	s_lshl_b32 s26, s14, 6
	s_ashr_i32 s27, s26, 31
	s_lshl_b64 s[26:27], s[26:27], 2
	s_add_u32 s26, s0, s26
	s_addc_u32 s27, s17, s27
	v_mov_b32_e32 v193, 0
	s_waitcnt lgkmcnt(0)
	v_mov_b64_e32 v[190:191], 0x1e8481
	global_load_dword v198, v193, s[26:27] sc1
	s_sleep 15
	s_branch .LBB0_599

.LBB0_599:
	global_load_dword v198, v193, s[26:27] sc1
	s_mov_b64 s[28:29], -1
	s_mov_b64 s[36:37], -1
	s_waitcnt vmcnt(1)
	v_readfirstlane_b32 s0, v198
	s_cmp_gt_u32 s0, 31
	s_cbranch_scc1 .LBB0_598
	s_memrealtime s[28:29]
	s_waitcnt lgkmcnt(0)
	s_sub_u32 s28, s28, s18
	s_subb_u32 s29, s29, s19
	v_cmp_lt_u64_e32 vcc, s[28:29], v[190:191]
	s_cbranch_vccz .LBB0_597
	s_mov_b64 s[36:37], 0
	s_sleep 2
	s_branch .LBB0_597

.LBB0_650:
	s_or_b64 exec, exec, s[12:13]
	s_andn2_b64 vcc, exec, s[20:21]
	s_cbranch_vccnz .LBB0_666
	s_memrealtime s[12:13]
	s_lshl_b32 s16, s14, 6
	s_ashr_i32 s17, s16, 31
	s_lshl_b64 s[16:17], s[16:17], 2
	s_add_u32 s16, s0, s16
	s_addc_u32 s17, s1, s17
	v_mov_b32_e32 v132, 0
	s_waitcnt lgkmcnt(0)
	v_mov_b64_e32 v[130:131], 0x1e8481
	global_load_dword v133, v132, s[16:17] sc1
	s_sleep 15
	s_branch .LBB0_654

.LBB0_654:
	global_load_dword v133, v132, s[16:17] sc1
	s_mov_b64 s[20:21], -1
	s_mov_b64 s[26:27], -1
	s_waitcnt vmcnt(1)
	v_readfirstlane_b32 s0, v133
	s_cmp_gt_u32 s0, 31
	s_cbranch_scc1 .LBB0_653
	s_memrealtime s[0:1]
	s_waitcnt lgkmcnt(0)
	s_sub_u32 s0, s0, s12
	s_subb_u32 s1, s1, s13
	v_cmp_lt_u64_e32 vcc, s[0:1], v[130:131]
	s_cbranch_vccz .LBB0_652
	s_mov_b64 s[26:27], 0
	s_sleep 2
	s_branch .LBB0_652

.LBB0_902:
	s_or_b64 exec, exec, s[10:11]
	s_cmp_gt_u32 s33, 63
	s_cbranch_scc1 .LBB0_918
	s_memrealtime s[10:11]
	s_lshl_b32 s12, s29, 6
	s_ashr_i32 s13, s12, 31
	s_lshl_b64 s[12:13], s[12:13], 2
	s_add_u32 s12, s5, s12
	s_addc_u32 s13, s7, s13
	v_mov_b32_e32 v185, 0
	v_mov_b64_e32 v[182:183], 0x1e8481
	global_load_dword v190, v185, s[12:13] sc1
	s_sleep 15
	s_branch .LBB0_906

.LBB0_906:
	global_load_dword v190, v185, s[12:13] sc1
	s_mov_b64 s[14:15], -1
	s_mov_b64 s[16:17], -1
	s_waitcnt vmcnt(1)
	v_readfirstlane_b32 s5, v190
	s_cmp_gt_u32 s5, 31
	s_cbranch_scc1 .LBB0_905
	s_memrealtime s[14:15]
	s_waitcnt lgkmcnt(0)
	s_sub_u32 s14, s14, s10
	s_subb_u32 s15, s15, s11
	v_cmp_lt_u64_e32 vcc, s[14:15], v[182:183]
	s_cbranch_vccz .LBB0_904
	s_mov_b64 s[16:17], 0
	s_sleep 2
	s_branch .LBB0_904
